# GEMM K-loop compute-segment edges: s_setprio moved to the far side of each barrier, redundant mid-block setprio pair and post-barrier lgkmcnt removed (fewer issue slots between barrier and MFMAs)
# speedup vs baseline: 1.0122x; 1.0122x over previous
; #define PG8_STAGE(bufoff, gbase, voff) do { _Pragma("unroll") for (int _i = 0; _i < 2; ++_i) \
;         __builtin_amdgcn_global_load_lds((const unsigned*)((const char*)(gbase) + (voff)[_i]), (PG8_LAS unsigned*)(lds + (bufoff) + ldsw + _i * 8192), 16, 0, 0); } while (0)
; #define PG8_LDA(dst, b, h) do { _Pragma("unroll") for (int m = 0; m < 4; ++m) _Pragma("unroll") for (int k = 0; k < 2; ++k) dst[m][k] = *(const PG8_LAS bf16x8*)(lds + PG8_SA(b, h) + aoff + m * 2048 + k * 1024); } while (0)
; #define PG8_LDB(dst, b, h) do { _Pragma("unroll") for (int n = 0; n < 2; ++n) _Pragma("unroll") for (int k = 0; k < 2; ++k) dst[n][k] = *(const PG8_LAS bf16x8*)(lds + PG8_SB(b, h) + boff + n * 2048 + k * 1024); } while (0)
; #define PG8_MMA(ai, bj, At, Bt) do { __builtin_amdgcn_s_setprio(1); _Pragma("unroll") for (int m = 0; m < 4; ++m) _Pragma("unroll") for (int n = 0; n < 2; ++n) _Pragma("unroll") for (int k = 0; k < 2; ++k) \
;         acc[ai][bj][m][n] = __builtin_amdgcn_mfma_f32_16x16x32_bf16(Bt[n][k], At[m][k], acc[ai][bj][m][n], 0, 0, 0); __builtin_amdgcn_s_setprio(0); } while (0)
; #define PG8_WAIT_V(n) asm volatile("s_waitcnt vmcnt(" #n ")" ::: "memory")
; #define PG8_WAIT_L(n) asm volatile("s_waitcnt lgkmcnt(" #n ")" ::: "memory")
; template <class Epi, class Sched, bool ALIGN_EPI = false, bool SP2 = false>
; __device__ __forceinline__ void gemm_phase(PG8_LAS unsigned char* lds, const Gemm g, const Sched& S, const Epi& E) {
;     ...
;             const bool last = (t == nt - 2);
;             const char* a1 = cA + (size_t)(t + 1) * kstep;
;             const char* a2 = last ? nA : cA + (size_t)(t + 2) * kstep; const char* b2 = last ? nB : cB + (size_t)(t + 2) * kstep;
;             const char* a3 = a2 + kstep; const char* b3 = b2 + kstep;
;             if (last && has_next) S.a_ready(nxt);
;             if constexpr (SP2) {
;             PG8_LDB(B0, 0, 0); PG8_LDB(B1, 0, 1); PG8_SCHED; PG8_LDA(At, 0, 0); PG8_STAGE(PG8_SA(1, 1), a1 + hstep, voffA);
;             PG8_WAIT_V(8); PG8_WAIT_L(0); PG8_BAR; PG8_MMA(0, 0, At, B0); PG8_MMA(0, 1, At, B1); PG8_BAR; PG8_SCHED;
;             PG8_LDA(At, 0, 1); PG8_STAGE(PG8_SB(0, 0), b2, voffB); PG8_STAGE(PG8_SB(0, 1), b2 + hstep, voffB); PG8_STAGE(PG8_SA(0, 0), a2, voffA);
;             PG8_WAIT_V(8); PG8_WAIT_L(0); PG8_BAR; PG8_MMA(1, 0, At, B0); PG8_MMA(1, 1, At, B1); PG8_BAR; PG8_SCHED;
.LBB0_694:
	s_add_u32 s30, s28, 0xfffc0080
	s_addc_u32 s31, s29, -1
	s_add_i32 s46, 0, 0x10000
	s_cmp_eq_u32 s52, 12
	s_cselect_b32 s35, s21, s31
	s_cselect_b32 s34, vcc_lo, s30
	v_add_u32_e32 v140, s46, v142
	s_cselect_b32 s31, s19, s55
	s_cselect_b32 s30, vcc_hi, s54
	s_add_i32 s94, 0, 0x14000
	ds_read_b128 v[146:149], v140
	ds_read_b128 v[150:153], v140 offset:1024
	ds_read_b128 v[154:157], v140 offset:2048
	ds_read_b128 v[158:161], v140 offset:3072
	v_add_u32_e32 v140, s94, v142
	ds_read_b128 v[162:165], v140
	ds_read_b128 v[166:169], v140 offset:1024
	ds_read_b128 v[170:173], v140 offset:2048
	ds_read_b128 v[174:177], v140 offset:3072
	v_lshl_add_u64 v[194:195], s[28:29], 0, v[136:137]
	s_add_i32 m0, s27, 0xc000
	ds_read_b128 v[178:181], v144
	ds_read_b128 v[182:185], v144 offset:1024
	ds_read_b128 v[186:189], v144 offset:2048
	ds_read_b128 v[190:193], v144 offset:3072
	ds_read_b128 v[204:207], v144 offset:4096
	ds_read_b128 v[208:211], v144 offset:5120
	ds_read_b128 v[212:215], v144 offset:6144
	ds_read_b128 v[216:219], v144 offset:7168
	global_load_lds_dwordx4 v[194:195], off
	v_lshl_add_u64 v[194:195], s[28:29], 0, v[138:139]
	s_add_i32 m0, s27, 0xe000
	s_nop 0
	global_load_lds_dwordx4 v[194:195], off
	s_waitcnt vmcnt(8)
	s_waitcnt lgkmcnt(0)
	s_setprio 1
	s_barrier
	v_mfma_f32_16x16x32_bf16 v[128:131], v[146:149], v[178:181], v[128:131]
	v_mfma_f32_16x16x32_bf16 v[124:127], v[154:157], v[178:181], v[124:127]
	v_mfma_f32_16x16x32_bf16 v[116:119], v[146:149], v[186:189], v[116:119]
	v_mfma_f32_16x16x32_bf16 v[108:111], v[154:157], v[186:189], v[108:111]
	v_mfma_f32_16x16x32_bf16 v[100:103], v[146:149], v[204:207], v[100:103]
	v_mfma_f32_16x16x32_bf16 v[92:95], v[154:157], v[204:207], v[92:95]
	v_mfma_f32_16x16x32_bf16 v[84:87], v[146:149], v[212:215], v[84:87]
	v_mfma_f32_16x16x32_bf16 v[76:79], v[154:157], v[212:215], v[76:79]
	v_mfma_f32_16x16x32_bf16 v[128:131], v[150:153], v[182:185], v[128:131]
	v_mfma_f32_16x16x32_bf16 v[124:127], v[158:161], v[182:185], v[124:127]
	v_mfma_f32_16x16x32_bf16 v[116:119], v[150:153], v[190:193], v[116:119]
	v_mfma_f32_16x16x32_bf16 v[108:111], v[158:161], v[190:193], v[108:111]
	v_mfma_f32_16x16x32_bf16 v[100:103], v[150:153], v[208:211], v[100:103]
	v_mfma_f32_16x16x32_bf16 v[92:95], v[158:161], v[208:211], v[92:95]
	v_mfma_f32_16x16x32_bf16 v[84:87], v[150:153], v[216:219], v[84:87]
	v_mfma_f32_16x16x32_bf16 v[76:79], v[158:161], v[216:219], v[76:79]
	v_mfma_f32_16x16x32_bf16 v[120:123], v[162:165], v[178:181], v[120:123]
	v_mfma_f32_16x16x32_bf16 v[112:115], v[170:173], v[178:181], v[112:115]
	v_mfma_f32_16x16x32_bf16 v[104:107], v[162:165], v[186:189], v[104:107]
	v_mfma_f32_16x16x32_bf16 v[96:99], v[170:173], v[186:189], v[96:99]
	v_mfma_f32_16x16x32_bf16 v[88:91], v[162:165], v[204:207], v[88:91]
	v_mfma_f32_16x16x32_bf16 v[80:83], v[170:173], v[204:207], v[80:83]
	v_mfma_f32_16x16x32_bf16 v[72:75], v[162:165], v[212:215], v[72:75]
	v_mfma_f32_16x16x32_bf16 v[68:71], v[170:173], v[212:215], v[68:71]
	v_mfma_f32_16x16x32_bf16 v[120:123], v[166:169], v[182:185], v[120:123]
	v_mfma_f32_16x16x32_bf16 v[112:115], v[174:177], v[182:185], v[112:115]
	v_mfma_f32_16x16x32_bf16 v[104:107], v[166:169], v[190:193], v[104:107]
	v_mfma_f32_16x16x32_bf16 v[96:99], v[174:177], v[190:193], v[96:99]
	v_mfma_f32_16x16x32_bf16 v[88:91], v[166:169], v[208:211], v[88:91]
	v_mfma_f32_16x16x32_bf16 v[80:83], v[174:177], v[208:211], v[80:83]
	v_mfma_f32_16x16x32_bf16 v[72:75], v[166:169], v[216:219], v[72:75]
	v_mfma_f32_16x16x32_bf16 v[68:71], v[174:177], v[216:219], v[68:71]
	s_barrier
	s_setprio 0
	s_add_i32 s46, s46, s85
	v_lshl_add_u64 v[194:195], s[30:31], 0, v[2:3]
	s_mov_b32 m0, s46
	ds_read_b128 v[178:181], v144 offset:16384
	ds_read_b128 v[182:185], v144 offset:17408
	ds_read_b128 v[186:189], v144 offset:18432
	ds_read_b128 v[190:193], v144 offset:19456
	ds_read_b128 v[204:207], v144 offset:20480
	ds_read_b128 v[208:211], v144 offset:21504
	ds_read_b128 v[212:215], v144 offset:22528
	ds_read_b128 v[216:219], v144 offset:23552
	global_load_lds_dwordx4 v[194:195], off
	s_add_i32 m0, s46, 0x2000
	s_add_u32 s46, s30, 0x40000
	v_lshl_add_u64 v[236:237], s[30:31], 0, v[134:135]
	s_addc_u32 s47, s31, 0
	s_add_i32 s94, s94, s85
	global_load_lds_dwordx4 v[236:237], off
	v_lshl_add_u64 v[238:239], s[46:47], 0, v[2:3]
	s_mov_b32 m0, s94
	v_lshl_add_u64 v[240:241], s[34:35], 0, v[132:133]
	global_load_lds_dwordx4 v[238:239], off
	v_lshl_add_u64 v[238:239], s[46:47], 0, v[134:135]
	s_add_i32 m0, s94, 0x2000
	s_nop 0
	global_load_lds_dwordx4 v[238:239], off
	v_lshl_add_u64 v[238:239], s[34:35], 0, v[0:1]
	s_mov_b32 m0, s27
	s_nop 0
	global_load_lds_dwordx4 v[238:239], off
	s_mov_b32 m0, s68
	s_nop 0
	global_load_lds_dwordx4 v[240:241], off
	s_waitcnt vmcnt(8)
	s_waitcnt lgkmcnt(0)
	s_setprio 1
	s_barrier
; #define PG8_STAGE(bufoff, gbase, voff) do { _Pragma("unroll") for (int _i = 0; _i < 2; ++_i) \
;         __builtin_amdgcn_global_load_lds((const unsigned*)((const char*)(gbase) + (voff)[_i]), (PG8_LAS unsigned*)(lds + (bufoff) + ldsw + _i * 8192), 16, 0, 0); } while (0)
; #define PG8_LDA(dst, b, h) do { _Pragma("unroll") for (int m = 0; m < 4; ++m) _Pragma("unroll") for (int k = 0; k < 2; ++k) dst[m][k] = *(const PG8_LAS bf16x8*)(lds + PG8_SA(b, h) + aoff + m * 2048 + k * 1024); } while (0)
; #define PG8_LDB(dst, b, h) do { _Pragma("unroll") for (int n = 0; n < 2; ++n) _Pragma("unroll") for (int k = 0; k < 2; ++k) dst[n][k] = *(const PG8_LAS bf16x8*)(lds + PG8_SB(b, h) + boff + n * 2048 + k * 1024); } while (0)
; #define PG8_MMA(ai, bj, At, Bt) do { __builtin_amdgcn_s_setprio(1); _Pragma("unroll") for (int m = 0; m < 4; ++m) _Pragma("unroll") for (int n = 0; n < 2; ++n) _Pragma("unroll") for (int k = 0; k < 2; ++k) \
;         acc[ai][bj][m][n] = __builtin_amdgcn_mfma_f32_16x16x32_bf16(Bt[n][k], At[m][k], acc[ai][bj][m][n], 0, 0, 0); __builtin_amdgcn_s_setprio(0); } while (0)
; #define PG8_WAIT_V(n) asm volatile("s_waitcnt vmcnt(" #n ")" ::: "memory")
; #define PG8_WAIT_L(n) asm volatile("s_waitcnt lgkmcnt(" #n ")" ::: "memory")
; #define PG8_BAR __builtin_amdgcn_s_barrier()
; #define PG8_SCHED __builtin_amdgcn_sched_barrier(0)
; template <class Epi, class Sched, bool ALIGN_EPI = false, bool SP2 = false>
; __device__ __forceinline__ void gemm_phase(PG8_LAS unsigned char* lds, const Gemm g, const Sched& S, const Epi& E) {
;     ...
;             PG8_WAIT_V(8); PG8_WAIT_L(0); PG8_BAR; PG8_MMA(1, 0, At, B0); PG8_MMA(1, 1, At, B1); PG8_BAR; PG8_SCHED;
;             PG8_LDB(B0, 1, 0); PG8_LDB(B1, 1, 1); PG8_SCHED; PG8_LDA(At, 1, 0); PG8_STAGE(PG8_SA(0, 1), a2 + hstep, voffA);
;             PG8_WAIT_V(8); PG8_WAIT_L(0); PG8_BAR; PG8_MMA(0, 0, At, B0); PG8_MMA(0, 1, At, B1); PG8_BAR; PG8_SCHED;
	v_mfma_f32_16x16x32_bf16 v[64:67], v[146:149], v[178:181], v[64:67]
	v_mfma_f32_16x16x32_bf16 v[60:63], v[154:157], v[178:181], v[60:63]
	v_mfma_f32_16x16x32_bf16 v[52:55], v[146:149], v[186:189], v[52:55]
	v_mfma_f32_16x16x32_bf16 v[44:47], v[154:157], v[186:189], v[44:47]
	v_mfma_f32_16x16x32_bf16 v[36:39], v[146:149], v[204:207], v[36:39]
	v_mfma_f32_16x16x32_bf16 v[28:31], v[154:157], v[204:207], v[28:31]
	v_mfma_f32_16x16x32_bf16 v[20:23], v[146:149], v[212:215], v[20:23]
	v_mfma_f32_16x16x32_bf16 v[12:15], v[154:157], v[212:215], v[12:15]
	v_mfma_f32_16x16x32_bf16 v[64:67], v[150:153], v[182:185], v[64:67]
	v_mfma_f32_16x16x32_bf16 v[60:63], v[158:161], v[182:185], v[60:63]
	v_mfma_f32_16x16x32_bf16 v[52:55], v[150:153], v[190:193], v[52:55]
	v_mfma_f32_16x16x32_bf16 v[44:47], v[158:161], v[190:193], v[44:47]
	v_mfma_f32_16x16x32_bf16 v[36:39], v[150:153], v[208:211], v[36:39]
	v_mfma_f32_16x16x32_bf16 v[28:31], v[158:161], v[208:211], v[28:31]
	v_mfma_f32_16x16x32_bf16 v[20:23], v[150:153], v[216:219], v[20:23]
	v_mfma_f32_16x16x32_bf16 v[12:15], v[158:161], v[216:219], v[12:15]
	v_mfma_f32_16x16x32_bf16 v[56:59], v[162:165], v[178:181], v[56:59]
	v_mfma_f32_16x16x32_bf16 v[48:51], v[170:173], v[178:181], v[48:51]
	v_mfma_f32_16x16x32_bf16 v[40:43], v[162:165], v[186:189], v[40:43]
	v_mfma_f32_16x16x32_bf16 v[32:35], v[170:173], v[186:189], v[32:35]
	v_mfma_f32_16x16x32_bf16 v[24:27], v[162:165], v[204:207], v[24:27]
	v_mfma_f32_16x16x32_bf16 v[16:19], v[170:173], v[204:207], v[16:19]
	v_mfma_f32_16x16x32_bf16 v[8:11], v[162:165], v[212:215], v[8:11]
	v_mfma_f32_16x16x32_bf16 v[4:7], v[170:173], v[212:215], v[4:7]
	v_mfma_f32_16x16x32_bf16 v[56:59], v[166:169], v[182:185], v[56:59]
	v_mfma_f32_16x16x32_bf16 v[48:51], v[174:177], v[182:185], v[48:51]
	v_mfma_f32_16x16x32_bf16 v[40:43], v[166:169], v[190:193], v[40:43]
	v_mfma_f32_16x16x32_bf16 v[32:35], v[174:177], v[190:193], v[32:35]
	v_mfma_f32_16x16x32_bf16 v[24:27], v[166:169], v[208:211], v[24:27]
	v_mfma_f32_16x16x32_bf16 v[16:19], v[174:177], v[208:211], v[16:19]
	v_mfma_f32_16x16x32_bf16 v[8:11], v[166:169], v[216:219], v[8:11]
	v_mfma_f32_16x16x32_bf16 v[4:7], v[174:177], v[216:219], v[4:7]
	s_barrier
	s_setprio 0
	s_add_i32 s46, 0, 0x18000
	v_add_u32_e32 v140, s46, v142
	s_add_i32 s47, 0, 0x1c000
	ds_read_b128 v[146:149], v140
	ds_read_b128 v[150:153], v140 offset:1024
	ds_read_b128 v[154:157], v140 offset:2048
	ds_read_b128 v[158:161], v140 offset:3072
	v_add_u32_e32 v140, s47, v142
	ds_read_b128 v[162:165], v140
	ds_read_b128 v[166:169], v140 offset:1024
	ds_read_b128 v[170:173], v140 offset:2048
	ds_read_b128 v[174:177], v140 offset:3072
	s_add_u32 s34, s34, 0x40000
	s_addc_u32 s35, s35, 0
	s_mov_b32 m0, s69
	v_lshl_add_u64 v[242:243], s[34:35], 0, v[0:1]
	ds_read_b128 v[178:181], v144 offset:32768
	ds_read_b128 v[182:185], v144 offset:33792
	ds_read_b128 v[186:189], v144 offset:34816
	ds_read_b128 v[190:193], v144 offset:35840
	ds_read_b128 v[204:207], v144 offset:36864
	ds_read_b128 v[208:211], v144 offset:37888
	ds_read_b128 v[212:215], v144 offset:38912
	ds_read_b128 v[216:219], v144 offset:39936
	global_load_lds_dwordx4 v[242:243], off
	v_lshl_add_u64 v[242:243], s[34:35], 0, v[132:133]
	s_mov_b32 m0, s33
	s_nop 0
	global_load_lds_dwordx4 v[242:243], off
	s_waitcnt vmcnt(8)
	s_waitcnt lgkmcnt(0)
	s_setprio 1
	s_barrier
	v_mfma_f32_16x16x32_bf16 v[128:131], v[146:149], v[178:181], v[128:131]
	v_mfma_f32_16x16x32_bf16 v[124:127], v[154:157], v[178:181], v[124:127]
	v_mfma_f32_16x16x32_bf16 v[116:119], v[146:149], v[186:189], v[116:119]
	v_mfma_f32_16x16x32_bf16 v[108:111], v[154:157], v[186:189], v[108:111]
	v_mfma_f32_16x16x32_bf16 v[100:103], v[146:149], v[204:207], v[100:103]
	v_mfma_f32_16x16x32_bf16 v[92:95], v[154:157], v[204:207], v[92:95]
	v_mfma_f32_16x16x32_bf16 v[84:87], v[146:149], v[212:215], v[84:87]
	v_mfma_f32_16x16x32_bf16 v[76:79], v[154:157], v[212:215], v[76:79]
	v_mfma_f32_16x16x32_bf16 v[128:131], v[150:153], v[182:185], v[128:131]
	v_mfma_f32_16x16x32_bf16 v[124:127], v[158:161], v[182:185], v[124:127]
	v_mfma_f32_16x16x32_bf16 v[116:119], v[150:153], v[190:193], v[116:119]
	v_mfma_f32_16x16x32_bf16 v[108:111], v[158:161], v[190:193], v[108:111]
	v_mfma_f32_16x16x32_bf16 v[100:103], v[150:153], v[208:211], v[100:103]
	v_mfma_f32_16x16x32_bf16 v[92:95], v[158:161], v[208:211], v[92:95]
	v_mfma_f32_16x16x32_bf16 v[84:87], v[150:153], v[216:219], v[84:87]
	v_mfma_f32_16x16x32_bf16 v[76:79], v[158:161], v[216:219], v[76:79]
	v_mfma_f32_16x16x32_bf16 v[120:123], v[162:165], v[178:181], v[120:123]
	v_mfma_f32_16x16x32_bf16 v[112:115], v[170:173], v[178:181], v[112:115]
	v_mfma_f32_16x16x32_bf16 v[104:107], v[162:165], v[186:189], v[104:107]
	v_mfma_f32_16x16x32_bf16 v[96:99], v[170:173], v[186:189], v[96:99]
	v_mfma_f32_16x16x32_bf16 v[88:91], v[162:165], v[204:207], v[88:91]
	v_mfma_f32_16x16x32_bf16 v[80:83], v[170:173], v[204:207], v[80:83]
	v_mfma_f32_16x16x32_bf16 v[72:75], v[162:165], v[212:215], v[72:75]
	v_mfma_f32_16x16x32_bf16 v[68:71], v[170:173], v[212:215], v[68:71]
	v_mfma_f32_16x16x32_bf16 v[120:123], v[166:169], v[182:185], v[120:123]
	v_mfma_f32_16x16x32_bf16 v[112:115], v[174:177], v[182:185], v[112:115]
	v_mfma_f32_16x16x32_bf16 v[104:107], v[166:169], v[190:193], v[104:107]
	v_mfma_f32_16x16x32_bf16 v[96:99], v[174:177], v[190:193], v[96:99]
	v_mfma_f32_16x16x32_bf16 v[88:91], v[166:169], v[208:211], v[88:91]
	v_mfma_f32_16x16x32_bf16 v[80:83], v[174:177], v[208:211], v[80:83]
	v_mfma_f32_16x16x32_bf16 v[72:75], v[166:169], v[216:219], v[72:75]
	v_mfma_f32_16x16x32_bf16 v[68:71], v[174:177], v[216:219], v[68:71]
	s_barrier
; #define PG8_STAGE(bufoff, gbase, voff) do { _Pragma("unroll") for (int _i = 0; _i < 2; ++_i) \
;         __builtin_amdgcn_global_load_lds((const unsigned*)((const char*)(gbase) + (voff)[_i]), (PG8_LAS unsigned*)(lds + (bufoff) + ldsw + _i * 8192), 16, 0, 0); } while (0)
; #define PG8_LDA(dst, b, h) do { _Pragma("unroll") for (int m = 0; m < 4; ++m) _Pragma("unroll") for (int k = 0; k < 2; ++k) dst[m][k] = *(const PG8_LAS bf16x8*)(lds + PG8_SA(b, h) + aoff + m * 2048 + k * 1024); } while (0)
; #define PG8_MMA(ai, bj, At, Bt) do { __builtin_amdgcn_s_setprio(1); _Pragma("unroll") for (int m = 0; m < 4; ++m) _Pragma("unroll") for (int n = 0; n < 2; ++n) _Pragma("unroll") for (int k = 0; k < 2; ++k) \
;         acc[ai][bj][m][n] = __builtin_amdgcn_mfma_f32_16x16x32_bf16(Bt[n][k], At[m][k], acc[ai][bj][m][n], 0, 0, 0); __builtin_amdgcn_s_setprio(0); } while (0)
; #define PG8_WAIT_V(n) asm volatile("s_waitcnt vmcnt(" #n ")" ::: "memory")
; #define PG8_WAIT_L(n) asm volatile("s_waitcnt lgkmcnt(" #n ")" ::: "memory")
; #define PG8_BAR __builtin_amdgcn_s_barrier()
; #define PG8_SCHED __builtin_amdgcn_sched_barrier(0)
; template <class Epi, class Sched, bool ALIGN_EPI = false, bool SP2 = false>
; __device__ __forceinline__ void gemm_phase(PG8_LAS unsigned char* lds, const Gemm g, const Sched& S, const Epi& E) {
;     ...
;             PG8_LDA(At, 1, 1); PG8_STAGE(PG8_SB(1, 0), b3, voffB); PG8_STAGE(PG8_SB(1, 1), b3 + hstep, voffB); PG8_STAGE(PG8_SA(1, 0), a3, voffA);
;             PG8_WAIT_V(8); PG8_WAIT_L(0); PG8_BAR; PG8_MMA(1, 0, At, B0); PG8_MMA(1, 1, At, B1); PG8_BAR; PG8_SCHED;
	s_setprio 0
	s_add_i32 s34, s46, s85
	v_lshl_add_u64 v[194:195], v[194:195], 0, s[42:43]
	s_mov_b32 m0, s34
	ds_read_b128 v[178:181], v144 offset:49152
	ds_read_b128 v[182:185], v144 offset:50176
	ds_read_b128 v[186:189], v144 offset:51200
	ds_read_b128 v[190:193], v144 offset:52224
	ds_read_b128 v[204:207], v144 offset:53248
	ds_read_b128 v[208:211], v144 offset:54272
	ds_read_b128 v[212:215], v144 offset:55296
	ds_read_b128 v[216:219], v144 offset:56320
	global_load_lds_dwordx4 v[194:195], off
	s_add_i32 m0, s34, 0x2000
	s_add_u32 s30, s30, 0x40080
	v_lshl_add_u64 v[194:195], v[236:237], 0, s[42:43]
	s_addc_u32 s31, s31, 0
	s_add_i32 s34, s47, s85
	global_load_lds_dwordx4 v[194:195], off
	v_lshl_add_u64 v[194:195], s[30:31], 0, v[2:3]
	s_mov_b32 m0, s34
	s_nop 0
	global_load_lds_dwordx4 v[194:195], off
	v_lshl_add_u64 v[194:195], s[30:31], 0, v[134:135]
	s_add_i32 m0, s34, 0x2000
	s_nop 0
	global_load_lds_dwordx4 v[194:195], off
	v_lshl_add_u64 v[194:195], v[238:239], 0, s[42:43]
	s_mov_b32 m0, s66
	s_nop 0
	global_load_lds_dwordx4 v[194:195], off
	v_lshl_add_u64 v[194:195], v[240:241], 0, s[42:43]
	s_mov_b32 m0, s67
	s_nop 0
	global_load_lds_dwordx4 v[194:195], off
	s_waitcnt vmcnt(8)
	s_waitcnt lgkmcnt(0)
	s_setprio 1
	s_barrier
	v_mfma_f32_16x16x32_bf16 v[64:67], v[146:149], v[178:181], v[64:67]
	v_mfma_f32_16x16x32_bf16 v[60:63], v[154:157], v[178:181], v[60:63]
	v_mfma_f32_16x16x32_bf16 v[52:55], v[146:149], v[186:189], v[52:55]
	v_mfma_f32_16x16x32_bf16 v[44:47], v[154:157], v[186:189], v[44:47]
	v_mfma_f32_16x16x32_bf16 v[36:39], v[146:149], v[204:207], v[36:39]
	v_mfma_f32_16x16x32_bf16 v[28:31], v[154:157], v[204:207], v[28:31]
	v_mfma_f32_16x16x32_bf16 v[20:23], v[146:149], v[212:215], v[20:23]
	v_mfma_f32_16x16x32_bf16 v[12:15], v[154:157], v[212:215], v[12:15]
	v_mfma_f32_16x16x32_bf16 v[64:67], v[150:153], v[182:185], v[64:67]
	v_mfma_f32_16x16x32_bf16 v[60:63], v[158:161], v[182:185], v[60:63]
	v_mfma_f32_16x16x32_bf16 v[52:55], v[150:153], v[190:193], v[52:55]
	v_mfma_f32_16x16x32_bf16 v[44:47], v[158:161], v[190:193], v[44:47]
	v_mfma_f32_16x16x32_bf16 v[36:39], v[150:153], v[208:211], v[36:39]
	v_mfma_f32_16x16x32_bf16 v[28:31], v[158:161], v[208:211], v[28:31]
	v_mfma_f32_16x16x32_bf16 v[20:23], v[150:153], v[216:219], v[20:23]
	v_mfma_f32_16x16x32_bf16 v[12:15], v[158:161], v[216:219], v[12:15]
	v_mfma_f32_16x16x32_bf16 v[56:59], v[162:165], v[178:181], v[56:59]
	v_mfma_f32_16x16x32_bf16 v[48:51], v[170:173], v[178:181], v[48:51]
	v_mfma_f32_16x16x32_bf16 v[40:43], v[162:165], v[186:189], v[40:43]
	v_mfma_f32_16x16x32_bf16 v[32:35], v[170:173], v[186:189], v[32:35]
	v_mfma_f32_16x16x32_bf16 v[24:27], v[162:165], v[204:207], v[24:27]
	v_mfma_f32_16x16x32_bf16 v[16:19], v[170:173], v[204:207], v[16:19]
	v_mfma_f32_16x16x32_bf16 v[8:11], v[162:165], v[212:215], v[8:11]
	v_mfma_f32_16x16x32_bf16 v[4:7], v[170:173], v[212:215], v[4:7]
	v_mfma_f32_16x16x32_bf16 v[56:59], v[166:169], v[182:185], v[56:59]
	v_mfma_f32_16x16x32_bf16 v[48:51], v[174:177], v[182:185], v[48:51]
	v_mfma_f32_16x16x32_bf16 v[40:43], v[166:169], v[190:193], v[40:43]
	v_mfma_f32_16x16x32_bf16 v[32:35], v[174:177], v[190:193], v[32:35]
	v_mfma_f32_16x16x32_bf16 v[24:27], v[166:169], v[208:211], v[24:27]
	v_mfma_f32_16x16x32_bf16 v[16:19], v[174:177], v[208:211], v[16:19]
	v_mfma_f32_16x16x32_bf16 v[8:11], v[166:169], v[216:219], v[8:11]
	v_mfma_f32_16x16x32_bf16 v[4:7], v[174:177], v[216:219], v[4:7]
	s_barrier
	s_setprio 0
	s_add_i32 s52, s52, 2
	s_add_u32 s28, s28, 0x100
	s_addc_u32 s29, s29, 0
	s_add_u32 s54, s54, 0x100
	s_addc_u32 s55, s55, 0
	s_cmp_gt_u32 s52, 13
	s_cbranch_scc0 .LBB0_694
	s_and_b64 vcc, exec, s[16:17]
	s_cbranch_vccz .LBB0_697
	s_barrier

; #define PG8_STAGE(bufoff, gbase, voff) do { _Pragma("unroll") for (int _i = 0; _i < 2; ++_i) \
;         __builtin_amdgcn_global_load_lds((const unsigned*)((const char*)(gbase) + (voff)[_i]), (PG8_LAS unsigned*)(lds + (bufoff) + ldsw + _i * 8192), 16, 0, 0); } while (0)
; #define PG8_LDA(dst, b, h) do { _Pragma("unroll") for (int m = 0; m < 4; ++m) _Pragma("unroll") for (int k = 0; k < 2; ++k) dst[m][k] = *(const PG8_LAS bf16x8*)(lds + PG8_SA(b, h) + aoff + m * 2048 + k * 1024); } while (0)
; #define PG8_LDB(dst, b, h) do { _Pragma("unroll") for (int n = 0; n < 2; ++n) _Pragma("unroll") for (int k = 0; k < 2; ++k) dst[n][k] = *(const PG8_LAS bf16x8*)(lds + PG8_SB(b, h) + boff + n * 2048 + k * 1024); } while (0)
; #define PG8_MMA(ai, bj, At, Bt) do { __builtin_amdgcn_s_setprio(1); _Pragma("unroll") for (int m = 0; m < 4; ++m) _Pragma("unroll") for (int n = 0; n < 2; ++n) _Pragma("unroll") for (int k = 0; k < 2; ++k) \
;         acc[ai][bj][m][n] = __builtin_amdgcn_mfma_f32_16x16x32_bf16(Bt[n][k], At[m][k], acc[ai][bj][m][n], 0, 0, 0); __builtin_amdgcn_s_setprio(0); } while (0)
; #define PG8_WAIT_V(n) asm volatile("s_waitcnt vmcnt(" #n ")" ::: "memory")
; #define PG8_WAIT_L(n) asm volatile("s_waitcnt lgkmcnt(" #n ")" ::: "memory")
; template <class Epi, class Sched, bool ALIGN_EPI = false, bool SP2 = false>
; __device__ __forceinline__ void gemm_phase(PG8_LAS unsigned char* lds, const Gemm g, const Sched& S, const Epi& E) {
;     ...
;             const bool last = (t == nt - 2);
;             const char* a1 = cA + (size_t)(t + 1) * kstep;
;             const char* a2 = last ? nA : cA + (size_t)(t + 2) * kstep; const char* b2 = last ? nB : cB + (size_t)(t + 2) * kstep;
;             const char* a3 = a2 + kstep; const char* b3 = b2 + kstep;
;             if (last && has_next) S.a_ready(nxt);
;             if constexpr (SP2) {
;             PG8_LDB(B0, 0, 0); PG8_LDB(B1, 0, 1); PG8_SCHED; PG8_LDA(At, 0, 0); PG8_STAGE(PG8_SA(1, 1), a1 + hstep, voffA);
;             PG8_WAIT_V(8); PG8_WAIT_L(0); PG8_BAR; PG8_MMA(0, 0, At, B0); PG8_MMA(0, 1, At, B1); PG8_BAR; PG8_SCHED;
;             PG8_LDA(At, 0, 1); PG8_STAGE(PG8_SB(0, 0), b2, voffB); PG8_STAGE(PG8_SB(0, 1), b2 + hstep, voffB); PG8_STAGE(PG8_SA(0, 0), a2, voffA);
;             PG8_WAIT_V(8); PG8_WAIT_L(0); PG8_BAR; PG8_MMA(1, 0, At, B0); PG8_MMA(1, 1, At, B1); PG8_BAR; PG8_SCHED;
.LBB0_720:
	s_add_i32 s40, s20, 2
	s_add_u32 s41, s12, s18
	s_addc_u32 s21, s13, s19
	s_add_u32 s46, s8, s18
	s_addc_u32 s47, s9, s19
	s_add_i32 s52, 0, 0x10000
	s_cmp_eq_u32 s78, s20
	s_cselect_b32 s21, s1, s21
	s_cselect_b32 s20, s0, s41
	v_add_u32_e32 v134, s52, v120
	s_cselect_b32 s49, s15, s47
	s_cselect_b32 s48, s14, s46
	s_add_i32 s41, 0, 0x14000
	ds_read_b128 v[122:125], v134
	ds_read_b128 v[126:129], v134 offset:1024
	ds_read_b128 v[130:133], v134 offset:2048
	ds_read_b128 v[140:143], v134 offset:3072
	v_add_u32_e32 v134, s41, v120
	ds_read_b128 v[164:167], v134
	ds_read_b128 v[168:171], v134 offset:1024
	ds_read_b128 v[172:175], v134 offset:2048
	ds_read_b128 v[176:179], v134 offset:3072
	v_lshl_add_u64 v[134:135], s[12:13], 0, v[110:111]
	s_add_i32 m0, s23, 0xc000
	ds_read_b128 v[180:183], v121
	ds_read_b128 v[184:187], v121 offset:1024
	ds_read_b128 v[188:191], v121 offset:2048
	ds_read_b128 v[192:195], v121 offset:3072
	ds_read_b128 v[208:211], v121 offset:4096
	ds_read_b128 v[212:215], v121 offset:5120
	ds_read_b128 v[236:239], v121 offset:6144
	ds_read_b128 v[240:243], v121 offset:7168
	global_load_lds_dwordx4 v[134:135], off
	v_lshl_add_u64 v[134:135], s[12:13], 0, v[108:109]
	s_add_i32 m0, s23, 0xe000
	s_nop 0
	global_load_lds_dwordx4 v[134:135], off
	s_waitcnt vmcnt(8)
	s_waitcnt lgkmcnt(0)
	s_setprio 1
	s_barrier
	v_mfma_f32_16x16x32_bf16 v[96:99], v[122:125], v[180:183], v[96:99]
	v_mfma_f32_16x16x32_bf16 v[160:163], v[130:133], v[180:183], v[160:163]
	v_mfma_f32_16x16x32_bf16 v[88:91], v[122:125], v[188:191], v[88:91]
	v_mfma_f32_16x16x32_bf16 v[156:159], v[130:133], v[188:191], v[156:159]
	v_mfma_f32_16x16x32_bf16 v[92:95], v[122:125], v[208:211], v[92:95]
	v_mfma_f32_16x16x32_bf16 v[152:155], v[130:133], v[208:211], v[152:155]
	v_mfma_f32_16x16x32_bf16 v[72:75], v[122:125], v[236:239], v[72:75]
	v_mfma_f32_16x16x32_bf16 v[148:151], v[130:133], v[236:239], v[148:151]
	v_mfma_f32_16x16x32_bf16 v[96:99], v[126:129], v[184:187], v[96:99]
	v_mfma_f32_16x16x32_bf16 v[160:163], v[140:143], v[184:187], v[160:163]
	v_mfma_f32_16x16x32_bf16 v[88:91], v[126:129], v[192:195], v[88:91]
	v_mfma_f32_16x16x32_bf16 v[156:159], v[140:143], v[192:195], v[156:159]
	v_mfma_f32_16x16x32_bf16 v[92:95], v[126:129], v[212:215], v[92:95]
	v_mfma_f32_16x16x32_bf16 v[152:155], v[140:143], v[212:215], v[152:155]
	v_mfma_f32_16x16x32_bf16 v[72:75], v[126:129], v[240:243], v[72:75]
	v_mfma_f32_16x16x32_bf16 v[148:151], v[140:143], v[240:243], v[148:151]
	v_mfma_f32_16x16x32_bf16 v[84:87], v[164:167], v[180:183], v[84:87]
	v_mfma_f32_16x16x32_bf16 v[32:35], v[172:175], v[180:183], v[32:35]
	v_mfma_f32_16x16x32_bf16 v[76:79], v[164:167], v[188:191], v[76:79]
	v_mfma_f32_16x16x32_bf16 v[28:31], v[172:175], v[188:191], v[28:31]
	v_mfma_f32_16x16x32_bf16 v[60:63], v[164:167], v[208:211], v[60:63]
	v_mfma_f32_16x16x32_bf16 v[24:27], v[172:175], v[208:211], v[24:27]
	v_mfma_f32_16x16x32_bf16 v[56:59], v[164:167], v[236:239], v[56:59]
	v_mfma_f32_16x16x32_bf16 v[20:23], v[172:175], v[236:239], v[20:23]
	v_mfma_f32_16x16x32_bf16 v[84:87], v[168:171], v[184:187], v[84:87]
	v_mfma_f32_16x16x32_bf16 v[32:35], v[176:179], v[184:187], v[32:35]
	v_mfma_f32_16x16x32_bf16 v[76:79], v[168:171], v[192:195], v[76:79]
	v_mfma_f32_16x16x32_bf16 v[28:31], v[176:179], v[192:195], v[28:31]
	v_mfma_f32_16x16x32_bf16 v[60:63], v[168:171], v[212:215], v[60:63]
	v_mfma_f32_16x16x32_bf16 v[24:27], v[176:179], v[212:215], v[24:27]
	v_mfma_f32_16x16x32_bf16 v[56:59], v[168:171], v[240:243], v[56:59]
	v_mfma_f32_16x16x32_bf16 v[20:23], v[176:179], v[240:243], v[20:23]
	s_barrier
	s_setprio 0
	s_add_i32 s46, s52, s22
	v_lshl_add_u64 v[204:205], s[48:49], 0, v[2:3]
	s_mov_b32 m0, s46
	ds_read_b128 v[180:183], v121 offset:16384
	ds_read_b128 v[184:187], v121 offset:17408
	ds_read_b128 v[188:191], v121 offset:18432
	ds_read_b128 v[192:195], v121 offset:19456
	ds_read_b128 v[208:211], v121 offset:20480
	ds_read_b128 v[212:215], v121 offset:21504
	ds_read_b128 v[236:239], v121 offset:22528
	ds_read_b128 v[240:243], v121 offset:23552
	global_load_lds_dwordx4 v[204:205], off
	s_add_i32 m0, s46, 0x2000
	v_lshl_add_u64 v[216:217], s[48:49], 0, v[0:1]
	s_add_u32 s48, s48, s77
	s_addc_u32 s49, s49, 0
	s_add_i32 s41, s41, s22
	global_load_lds_dwordx4 v[216:217], off
	v_lshl_add_u64 v[244:245], s[48:49], 0, v[2:3]
	s_mov_b32 m0, s41
	v_lshl_add_u64 v[246:247], s[48:49], 0, v[0:1]
	global_load_lds_dwordx4 v[244:245], off
	s_add_i32 m0, s41, 0x2000
	v_lshl_add_u64 v[248:249], s[20:21], 0, v[102:103]
	global_load_lds_dwordx4 v[246:247], off
	s_mov_b32 m0, s23
	v_lshl_add_u64 v[250:251], s[20:21], 0, v[100:101]
	global_load_lds_dwordx4 v[248:249], off
	s_mov_b32 m0, s24
	s_nop 0
	global_load_lds_dwordx4 v[250:251], off
	s_waitcnt vmcnt(8)
	s_waitcnt lgkmcnt(0)
	s_setprio 1
	s_barrier
; #define PG8_STAGE(bufoff, gbase, voff) do { _Pragma("unroll") for (int _i = 0; _i < 2; ++_i) \
;         __builtin_amdgcn_global_load_lds((const unsigned*)((const char*)(gbase) + (voff)[_i]), (PG8_LAS unsigned*)(lds + (bufoff) + ldsw + _i * 8192), 16, 0, 0); } while (0)
; #define PG8_LDA(dst, b, h) do { _Pragma("unroll") for (int m = 0; m < 4; ++m) _Pragma("unroll") for (int k = 0; k < 2; ++k) dst[m][k] = *(const PG8_LAS bf16x8*)(lds + PG8_SA(b, h) + aoff + m * 2048 + k * 1024); } while (0)
; #define PG8_LDB(dst, b, h) do { _Pragma("unroll") for (int n = 0; n < 2; ++n) _Pragma("unroll") for (int k = 0; k < 2; ++k) dst[n][k] = *(const PG8_LAS bf16x8*)(lds + PG8_SB(b, h) + boff + n * 2048 + k * 1024); } while (0)
; #define PG8_MMA(ai, bj, At, Bt) do { __builtin_amdgcn_s_setprio(1); _Pragma("unroll") for (int m = 0; m < 4; ++m) _Pragma("unroll") for (int n = 0; n < 2; ++n) _Pragma("unroll") for (int k = 0; k < 2; ++k) \
;         acc[ai][bj][m][n] = __builtin_amdgcn_mfma_f32_16x16x32_bf16(Bt[n][k], At[m][k], acc[ai][bj][m][n], 0, 0, 0); __builtin_amdgcn_s_setprio(0); } while (0)
; #define PG8_WAIT_V(n) asm volatile("s_waitcnt vmcnt(" #n ")" ::: "memory")
; #define PG8_WAIT_L(n) asm volatile("s_waitcnt lgkmcnt(" #n ")" ::: "memory")
; #define PG8_BAR __builtin_amdgcn_s_barrier()
; #define PG8_SCHED __builtin_amdgcn_sched_barrier(0)
; template <class Epi, class Sched, bool ALIGN_EPI = false, bool SP2 = false>
; __device__ __forceinline__ void gemm_phase(PG8_LAS unsigned char* lds, const Gemm g, const Sched& S, const Epi& E) {
;     ...
;             PG8_WAIT_V(8); PG8_WAIT_L(0); PG8_BAR; PG8_MMA(1, 0, At, B0); PG8_MMA(1, 1, At, B1); PG8_BAR; PG8_SCHED;
;             PG8_LDB(B0, 1, 0); PG8_LDB(B1, 1, 1); PG8_SCHED; PG8_LDA(At, 1, 0); PG8_STAGE(PG8_SA(0, 1), a2 + hstep, voffA);
;             PG8_WAIT_V(8); PG8_WAIT_L(0); PG8_BAR; PG8_MMA(0, 0, At, B0); PG8_MMA(0, 1, At, B1); PG8_BAR; PG8_SCHED;
	v_mfma_f32_16x16x32_bf16 v[80:83], v[122:125], v[180:183], v[80:83]
	v_mfma_f32_16x16x32_bf16 v[144:147], v[130:133], v[180:183], v[144:147]
	v_mfma_f32_16x16x32_bf16 v[64:67], v[122:125], v[188:191], v[64:67]
	v_mfma_f32_16x16x32_bf16 v[134:137], v[130:133], v[188:191], v[136:139]
	v_mfma_f32_16x16x32_bf16 v[68:71], v[122:125], v[208:211], v[68:71]
	v_mfma_f32_16x16x32_bf16 v[116:119], v[130:133], v[208:211], v[116:119]
	v_mfma_f32_16x16x32_bf16 v[52:55], v[122:125], v[236:239], v[52:55]
	v_mfma_f32_16x16x32_bf16 v[112:115], v[130:133], v[236:239], v[112:115]
	v_mfma_f32_16x16x32_bf16 v[80:83], v[126:129], v[184:187], v[80:83]
	v_mfma_f32_16x16x32_bf16 v[144:147], v[140:143], v[184:187], v[144:147]
	v_mfma_f32_16x16x32_bf16 v[64:67], v[126:129], v[192:195], v[64:67]
	v_mfma_f32_16x16x32_bf16 v[134:137], v[140:143], v[192:195], v[134:137]
	v_mfma_f32_16x16x32_bf16 v[68:71], v[126:129], v[212:215], v[68:71]
	v_mfma_f32_16x16x32_bf16 v[116:119], v[140:143], v[212:215], v[116:119]
	v_mfma_f32_16x16x32_bf16 v[52:55], v[126:129], v[240:243], v[52:55]
	v_mfma_f32_16x16x32_bf16 v[112:115], v[140:143], v[240:243], v[112:115]
	v_mfma_f32_16x16x32_bf16 v[48:51], v[164:167], v[180:183], v[48:51]
	v_mfma_f32_16x16x32_bf16 v[16:19], v[172:175], v[180:183], v[16:19]
	v_mfma_f32_16x16x32_bf16 v[44:47], v[164:167], v[188:191], v[44:47]
	v_mfma_f32_16x16x32_bf16 v[12:15], v[172:175], v[188:191], v[12:15]
	v_mfma_f32_16x16x32_bf16 v[40:43], v[164:167], v[208:211], v[40:43]
	v_mfma_f32_16x16x32_bf16 v[8:11], v[172:175], v[208:211], v[8:11]
	v_mfma_f32_16x16x32_bf16 v[36:39], v[164:167], v[236:239], v[36:39]
	v_mfma_f32_16x16x32_bf16 v[4:7], v[172:175], v[236:239], v[4:7]
	v_mfma_f32_16x16x32_bf16 v[48:51], v[168:171], v[184:187], v[48:51]
	v_mfma_f32_16x16x32_bf16 v[16:19], v[176:179], v[184:187], v[16:19]
	v_mfma_f32_16x16x32_bf16 v[44:47], v[168:171], v[192:195], v[44:47]
	v_mfma_f32_16x16x32_bf16 v[12:15], v[176:179], v[192:195], v[12:15]
	v_mfma_f32_16x16x32_bf16 v[40:43], v[168:171], v[212:215], v[40:43]
	v_mfma_f32_16x16x32_bf16 v[8:11], v[176:179], v[212:215], v[8:11]
	v_mfma_f32_16x16x32_bf16 v[36:39], v[168:171], v[240:243], v[36:39]
	v_mfma_f32_16x16x32_bf16 v[4:7], v[176:179], v[240:243], v[4:7]
	s_barrier
	s_setprio 0
	s_add_i32 s41, 0, 0x18000
	v_add_u32_e32 v138, s41, v120
	s_add_i32 s46, 0, 0x1c000
	ds_read_b128 v[122:125], v138
	ds_read_b128 v[126:129], v138 offset:1024
	ds_read_b128 v[130:133], v138 offset:2048
	ds_read_b128 v[140:143], v138 offset:3072
	v_add_u32_e32 v138, s46, v120
	ds_read_b128 v[164:167], v138
	ds_read_b128 v[168:171], v138 offset:1024
	ds_read_b128 v[172:175], v138 offset:2048
	ds_read_b128 v[176:179], v138 offset:3072
	s_add_u32 s20, s20, s77
	s_addc_u32 s21, s21, 0
	s_mov_b32 m0, s25
	v_lshl_add_u64 v[138:139], s[20:21], 0, v[102:103]
	ds_read_b128 v[180:183], v121 offset:32768
	ds_read_b128 v[184:187], v121 offset:33792
	ds_read_b128 v[188:191], v121 offset:34816
	ds_read_b128 v[192:195], v121 offset:35840
	ds_read_b128 v[208:211], v121 offset:36864
	ds_read_b128 v[212:215], v121 offset:37888
	ds_read_b128 v[236:239], v121 offset:38912
	ds_read_b128 v[240:243], v121 offset:39936
	global_load_lds_dwordx4 v[138:139], off
	v_lshl_add_u64 v[138:139], s[20:21], 0, v[100:101]
	s_mov_b32 m0, s27
	s_nop 0
	global_load_lds_dwordx4 v[138:139], off
	s_waitcnt vmcnt(8)
	s_waitcnt lgkmcnt(0)
	s_setprio 1
	s_barrier
	v_mfma_f32_16x16x32_bf16 v[96:99], v[122:125], v[180:183], v[96:99]
	v_mfma_f32_16x16x32_bf16 v[160:163], v[130:133], v[180:183], v[160:163]
	v_mfma_f32_16x16x32_bf16 v[88:91], v[122:125], v[188:191], v[88:91]
	v_mfma_f32_16x16x32_bf16 v[156:159], v[130:133], v[188:191], v[156:159]
	v_mfma_f32_16x16x32_bf16 v[92:95], v[122:125], v[208:211], v[92:95]
	v_mfma_f32_16x16x32_bf16 v[152:155], v[130:133], v[208:211], v[152:155]
	v_mfma_f32_16x16x32_bf16 v[72:75], v[122:125], v[236:239], v[72:75]
	v_mfma_f32_16x16x32_bf16 v[148:151], v[130:133], v[236:239], v[148:151]
	v_mfma_f32_16x16x32_bf16 v[96:99], v[126:129], v[184:187], v[96:99]
	v_mfma_f32_16x16x32_bf16 v[160:163], v[140:143], v[184:187], v[160:163]
	v_mfma_f32_16x16x32_bf16 v[88:91], v[126:129], v[192:195], v[88:91]
	v_mfma_f32_16x16x32_bf16 v[156:159], v[140:143], v[192:195], v[156:159]
	v_mfma_f32_16x16x32_bf16 v[92:95], v[126:129], v[212:215], v[92:95]
	v_mfma_f32_16x16x32_bf16 v[152:155], v[140:143], v[212:215], v[152:155]
	v_mfma_f32_16x16x32_bf16 v[72:75], v[126:129], v[240:243], v[72:75]
	v_mfma_f32_16x16x32_bf16 v[148:151], v[140:143], v[240:243], v[148:151]
	v_mfma_f32_16x16x32_bf16 v[84:87], v[164:167], v[180:183], v[84:87]
	v_mfma_f32_16x16x32_bf16 v[32:35], v[172:175], v[180:183], v[32:35]
	v_mfma_f32_16x16x32_bf16 v[76:79], v[164:167], v[188:191], v[76:79]
	v_mfma_f32_16x16x32_bf16 v[28:31], v[172:175], v[188:191], v[28:31]
	v_mfma_f32_16x16x32_bf16 v[60:63], v[164:167], v[208:211], v[60:63]
	v_mfma_f32_16x16x32_bf16 v[24:27], v[172:175], v[208:211], v[24:27]
	v_mfma_f32_16x16x32_bf16 v[56:59], v[164:167], v[236:239], v[56:59]
	v_mfma_f32_16x16x32_bf16 v[20:23], v[172:175], v[236:239], v[20:23]
	v_mfma_f32_16x16x32_bf16 v[84:87], v[168:171], v[184:187], v[84:87]
	v_mfma_f32_16x16x32_bf16 v[32:35], v[176:179], v[184:187], v[32:35]
	v_mfma_f32_16x16x32_bf16 v[76:79], v[168:171], v[192:195], v[76:79]
	v_mfma_f32_16x16x32_bf16 v[28:31], v[176:179], v[192:195], v[28:31]
	v_mfma_f32_16x16x32_bf16 v[60:63], v[168:171], v[212:215], v[60:63]
	v_mfma_f32_16x16x32_bf16 v[24:27], v[176:179], v[212:215], v[24:27]
	v_mfma_f32_16x16x32_bf16 v[56:59], v[168:171], v[240:243], v[56:59]
	v_mfma_f32_16x16x32_bf16 v[20:23], v[176:179], v[240:243], v[20:23]
	s_barrier
; #define PG8_STAGE(bufoff, gbase, voff) do { _Pragma("unroll") for (int _i = 0; _i < 2; ++_i) \
;         __builtin_amdgcn_global_load_lds((const unsigned*)((const char*)(gbase) + (voff)[_i]), (PG8_LAS unsigned*)(lds + (bufoff) + ldsw + _i * 8192), 16, 0, 0); } while (0)
; #define PG8_LDA(dst, b, h) do { _Pragma("unroll") for (int m = 0; m < 4; ++m) _Pragma("unroll") for (int k = 0; k < 2; ++k) dst[m][k] = *(const PG8_LAS bf16x8*)(lds + PG8_SA(b, h) + aoff + m * 2048 + k * 1024); } while (0)
; #define PG8_MMA(ai, bj, At, Bt) do { __builtin_amdgcn_s_setprio(1); _Pragma("unroll") for (int m = 0; m < 4; ++m) _Pragma("unroll") for (int n = 0; n < 2; ++n) _Pragma("unroll") for (int k = 0; k < 2; ++k) \
;         acc[ai][bj][m][n] = __builtin_amdgcn_mfma_f32_16x16x32_bf16(Bt[n][k], At[m][k], acc[ai][bj][m][n], 0, 0, 0); __builtin_amdgcn_s_setprio(0); } while (0)
; #define PG8_WAIT_V(n) asm volatile("s_waitcnt vmcnt(" #n ")" ::: "memory")
; #define PG8_WAIT_L(n) asm volatile("s_waitcnt lgkmcnt(" #n ")" ::: "memory")
; #define PG8_BAR __builtin_amdgcn_s_barrier()
; #define PG8_SCHED __builtin_amdgcn_sched_barrier(0)
; template <class Epi, class Sched, bool ALIGN_EPI = false, bool SP2 = false>
; __device__ __forceinline__ void gemm_phase(PG8_LAS unsigned char* lds, const Gemm g, const Sched& S, const Epi& E) {
;     ...
;             PG8_LDA(At, 1, 1); PG8_STAGE(PG8_SB(1, 0), b3, voffB); PG8_STAGE(PG8_SB(1, 1), b3 + hstep, voffB); PG8_STAGE(PG8_SA(1, 0), a3, voffA);
;             PG8_WAIT_V(8); PG8_WAIT_L(0); PG8_BAR; PG8_MMA(1, 0, At, B0); PG8_MMA(1, 1, At, B1); PG8_BAR; PG8_SCHED;
;     ...
;         if (!has_next) break;
; #pragma unroll
;         for (int a = 0; a < 2; ++a)
; #pragma unroll
;             for (int b = 0; b < 2; ++b)
; #pragma unroll
;                 for (int m = 0; m < 4; ++m)
; #pragma unroll
;                     for (int n = 0; n < 2; ++n) acc[a][b][m][n] = (f32x4){0.f, 0.f, 0.f, 0.f};
;         cur = nxt; cA = nA; cB = nB; ++ui;
	s_setprio 0
	s_add_i32 s20, s41, s22
	v_lshl_add_u64 v[138:139], v[204:205], 0, s[42:43]
	s_mov_b32 m0, s20
	ds_read_b128 v[180:183], v121 offset:49152
	ds_read_b128 v[184:187], v121 offset:50176
	ds_read_b128 v[188:191], v121 offset:51200
	ds_read_b128 v[192:195], v121 offset:52224
	ds_read_b128 v[208:211], v121 offset:53248
	ds_read_b128 v[212:215], v121 offset:54272
	ds_read_b128 v[236:239], v121 offset:55296
	ds_read_b128 v[240:243], v121 offset:56320
	global_load_lds_dwordx4 v[138:139], off
	v_lshl_add_u64 v[138:139], v[216:217], 0, s[42:43]
	s_add_i32 m0, s20, 0x2000
	s_add_i32 s20, s46, s22
	global_load_lds_dwordx4 v[138:139], off
	v_lshl_add_u64 v[138:139], v[244:245], 0, s[42:43]
	s_mov_b32 m0, s20
	s_nop 0
	global_load_lds_dwordx4 v[138:139], off
	v_lshl_add_u64 v[138:139], v[246:247], 0, s[42:43]
	s_add_i32 m0, s20, 0x2000
	s_nop 0
	global_load_lds_dwordx4 v[138:139], off
	v_lshl_add_u64 v[138:139], v[248:249], 0, s[42:43]
	s_mov_b32 m0, s28
	s_nop 0
	global_load_lds_dwordx4 v[138:139], off
	v_lshl_add_u64 v[138:139], v[250:251], 0, s[42:43]
	s_mov_b32 m0, s29
	s_nop 0
	global_load_lds_dwordx4 v[138:139], off
	s_waitcnt vmcnt(8)
	s_waitcnt lgkmcnt(0)
	s_setprio 1
	s_barrier
	v_mfma_f32_16x16x32_bf16 v[80:83], v[122:125], v[180:183], v[80:83]
	v_mfma_f32_16x16x32_bf16 v[144:147], v[130:133], v[180:183], v[144:147]
	v_mfma_f32_16x16x32_bf16 v[64:67], v[122:125], v[188:191], v[64:67]
	v_mfma_f32_16x16x32_bf16 v[134:137], v[130:133], v[188:191], v[134:137]
	v_mfma_f32_16x16x32_bf16 v[68:71], v[122:125], v[208:211], v[68:71]
	v_mfma_f32_16x16x32_bf16 v[116:119], v[130:133], v[208:211], v[116:119]
	v_mfma_f32_16x16x32_bf16 v[52:55], v[122:125], v[236:239], v[52:55]
	v_mfma_f32_16x16x32_bf16 v[112:115], v[130:133], v[236:239], v[112:115]
	v_mfma_f32_16x16x32_bf16 v[80:83], v[126:129], v[184:187], v[80:83]
	v_mfma_f32_16x16x32_bf16 v[144:147], v[140:143], v[184:187], v[144:147]
	v_mfma_f32_16x16x32_bf16 v[64:67], v[126:129], v[192:195], v[64:67]
	v_mfma_f32_16x16x32_bf16 v[136:139], v[140:143], v[192:195], v[134:137]
	v_mfma_f32_16x16x32_bf16 v[68:71], v[126:129], v[212:215], v[68:71]
	v_mfma_f32_16x16x32_bf16 v[116:119], v[140:143], v[212:215], v[116:119]
	v_mfma_f32_16x16x32_bf16 v[52:55], v[126:129], v[240:243], v[52:55]
	v_mfma_f32_16x16x32_bf16 v[112:115], v[140:143], v[240:243], v[112:115]
	v_mfma_f32_16x16x32_bf16 v[48:51], v[164:167], v[180:183], v[48:51]
	v_mfma_f32_16x16x32_bf16 v[16:19], v[172:175], v[180:183], v[16:19]
	v_mfma_f32_16x16x32_bf16 v[44:47], v[164:167], v[188:191], v[44:47]
	v_mfma_f32_16x16x32_bf16 v[12:15], v[172:175], v[188:191], v[12:15]
	v_mfma_f32_16x16x32_bf16 v[40:43], v[164:167], v[208:211], v[40:43]
	v_mfma_f32_16x16x32_bf16 v[8:11], v[172:175], v[208:211], v[8:11]
	v_mfma_f32_16x16x32_bf16 v[36:39], v[164:167], v[236:239], v[36:39]
	v_mfma_f32_16x16x32_bf16 v[4:7], v[172:175], v[236:239], v[4:7]
	v_mfma_f32_16x16x32_bf16 v[48:51], v[168:171], v[184:187], v[48:51]
	v_mfma_f32_16x16x32_bf16 v[16:19], v[176:179], v[184:187], v[16:19]
	v_mfma_f32_16x16x32_bf16 v[44:47], v[168:171], v[192:195], v[44:47]
	v_mfma_f32_16x16x32_bf16 v[12:15], v[176:179], v[192:195], v[12:15]
	v_mfma_f32_16x16x32_bf16 v[40:43], v[168:171], v[212:215], v[40:43]
	v_mfma_f32_16x16x32_bf16 v[8:11], v[176:179], v[212:215], v[8:11]
	v_mfma_f32_16x16x32_bf16 v[36:39], v[168:171], v[240:243], v[36:39]
	v_mfma_f32_16x16x32_bf16 v[4:7], v[176:179], v[240:243], v[4:7]
	s_barrier
	s_setprio 0
	s_add_u32 s18, s18, 0x100
	s_addc_u32 s19, s19, 0
	v_lshl_add_u64 v[110:111], v[110:111], 0, s[92:93]
	v_lshl_add_u64 v[108:109], v[108:109], 0, s[92:93]
	s_cmp_ge_u32 s40, s97
	s_mov_b32 s20, s40
	s_cbranch_scc0 .LBB0_720
	s_and_b64 vcc, exec, s[4:5]
	s_cbranch_vccnz .LBB0_708
	v_mov_b32_e32 v4, 0
	s_mov_b32 s10, s31
	s_mov_b32 s39, s34
	s_mov_b64 s[8:9], s[14:15]
	s_mov_b64 s[12:13], s[0:1]
	s_mov_b32 s30, s35
	v_mov_b32_e32 v5, v4
	v_mov_b32_e32 v6, v4
	v_mov_b32_e32 v7, v4
	v_mov_b32_e32 v36, v4
	v_mov_b32_e32 v37, v4
	v_mov_b32_e32 v38, v4
	v_mov_b32_e32 v39, v4
	v_mov_b32_e32 v8, v4
	v_mov_b32_e32 v9, v4
	v_mov_b32_e32 v10, v4
	v_mov_b32_e32 v11, v4
	v_mov_b32_e32 v40, v4
	v_mov_b32_e32 v41, v4
	v_mov_b32_e32 v42, v4
	v_mov_b32_e32 v43, v4
	v_mov_b32_e32 v12, v4
	v_mov_b32_e32 v13, v4
	v_mov_b32_e32 v14, v4
	v_mov_b32_e32 v15, v4
	v_mov_b32_e32 v44, v4
	v_mov_b32_e32 v45, v4
	v_mov_b32_e32 v46, v4
	v_mov_b32_e32 v47, v4
	v_mov_b32_e32 v16, v4
	v_mov_b32_e32 v17, v4
	v_mov_b32_e32 v18, v4
	v_mov_b32_e32 v19, v4
	v_mov_b32_e32 v48, v4
	v_mov_b32_e32 v49, v4
	v_mov_b32_e32 v50, v4
	v_mov_b32_e32 v51, v4
	v_mov_b32_e32 v112, v4
	v_mov_b32_e32 v113, v4
	v_mov_b32_e32 v114, v4
	v_mov_b32_e32 v115, v4
	v_mov_b32_e32 v52, v4
	v_mov_b32_e32 v53, v4
	v_mov_b32_e32 v54, v4
	v_mov_b32_e32 v55, v4
	v_mov_b32_e32 v116, v4
	v_mov_b32_e32 v117, v4
	v_mov_b32_e32 v118, v4
	v_mov_b32_e32 v119, v4
	v_mov_b32_e32 v68, v4
	v_mov_b32_e32 v69, v4
	v_mov_b32_e32 v70, v4
	v_mov_b32_e32 v71, v4
	v_mov_b32_e32 v136, v4
	v_mov_b32_e32 v137, v4
	v_mov_b32_e32 v138, v4
	v_mov_b32_e32 v139, v4
	v_mov_b32_e32 v64, v4
	v_mov_b32_e32 v65, v4
	v_mov_b32_e32 v66, v4
	v_mov_b32_e32 v67, v4
	v_mov_b32_e32 v144, v4
	v_mov_b32_e32 v145, v4
	v_mov_b32_e32 v146, v4
	v_mov_b32_e32 v147, v4
	v_mov_b32_e32 v80, v4
	v_mov_b32_e32 v81, v4
	v_mov_b32_e32 v82, v4
	v_mov_b32_e32 v83, v4
	v_mov_b32_e32 v20, v4
	v_mov_b32_e32 v21, v4
	v_mov_b32_e32 v22, v4
	v_mov_b32_e32 v23, v4
	v_mov_b32_e32 v56, v4
	v_mov_b32_e32 v57, v4
	v_mov_b32_e32 v58, v4
	v_mov_b32_e32 v59, v4
	v_mov_b32_e32 v24, v4
	v_mov_b32_e32 v25, v4
	v_mov_b32_e32 v26, v4
	v_mov_b32_e32 v27, v4
	v_mov_b32_e32 v60, v4
	v_mov_b32_e32 v61, v4
	v_mov_b32_e32 v62, v4
	v_mov_b32_e32 v63, v4
	v_mov_b32_e32 v28, v4
	v_mov_b32_e32 v29, v4
	v_mov_b32_e32 v30, v4
	v_mov_b32_e32 v31, v4
	v_mov_b32_e32 v76, v4
	v_mov_b32_e32 v77, v4
	v_mov_b32_e32 v78, v4
	v_mov_b32_e32 v79, v4
	v_mov_b32_e32 v32, v4
	v_mov_b32_e32 v33, v4
	v_mov_b32_e32 v34, v4
	v_mov_b32_e32 v35, v4
	v_mov_b32_e32 v84, v4
	v_mov_b32_e32 v85, v4
	v_mov_b32_e32 v86, v4
	v_mov_b32_e32 v87, v4
	v_mov_b32_e32 v148, v4
	v_mov_b32_e32 v149, v4
	v_mov_b32_e32 v150, v4
	v_mov_b32_e32 v151, v4
	v_mov_b32_e32 v72, v4
	v_mov_b32_e32 v73, v4
	v_mov_b32_e32 v74, v4
	v_mov_b32_e32 v75, v4
	v_mov_b32_e32 v152, v4
	v_mov_b32_e32 v153, v4
	v_mov_b32_e32 v154, v4
	v_mov_b32_e32 v155, v4
	v_mov_b32_e32 v92, v4
	v_mov_b32_e32 v93, v4
	v_mov_b32_e32 v94, v4
	v_mov_b32_e32 v95, v4
	v_mov_b32_e32 v156, v4
	v_mov_b32_e32 v157, v4
	v_mov_b32_e32 v158, v4
	v_mov_b32_e32 v159, v4
	v_mov_b32_e32 v88, v4
	v_mov_b32_e32 v89, v4
	v_mov_b32_e32 v90, v4
	v_mov_b32_e32 v91, v4
	v_mov_b32_e32 v160, v4
	v_mov_b32_e32 v161, v4
	v_mov_b32_e32 v162, v4
	v_mov_b32_e32 v163, v4
	v_mov_b32_e32 v96, v4
	v_mov_b32_e32 v97, v4
	v_mov_b32_e32 v98, v4
	v_mov_b32_e32 v99, v4
	s_branch .LBB0_708

; #define PG8_STAGE(bufoff, gbase, voff) do { _Pragma("unroll") for (int _i = 0; _i < 2; ++_i) \
;         __builtin_amdgcn_global_load_lds((const unsigned*)((const char*)(gbase) + (voff)[_i]), (PG8_LAS unsigned*)(lds + (bufoff) + ldsw + _i * 8192), 16, 0, 0); } while (0)
; #define PG8_LDA(dst, b, h) do { _Pragma("unroll") for (int m = 0; m < 4; ++m) _Pragma("unroll") for (int k = 0; k < 2; ++k) dst[m][k] = *(const PG8_LAS bf16x8*)(lds + PG8_SA(b, h) + aoff + m * 2048 + k * 1024); } while (0)
; #define PG8_LDB(dst, b, h) do { _Pragma("unroll") for (int n = 0; n < 2; ++n) _Pragma("unroll") for (int k = 0; k < 2; ++k) dst[n][k] = *(const PG8_LAS bf16x8*)(lds + PG8_SB(b, h) + boff + n * 2048 + k * 1024); } while (0)
; #define PG8_MMA(ai, bj, At, Bt) do { __builtin_amdgcn_s_setprio(1); _Pragma("unroll") for (int m = 0; m < 4; ++m) _Pragma("unroll") for (int n = 0; n < 2; ++n) _Pragma("unroll") for (int k = 0; k < 2; ++k) \
;         acc[ai][bj][m][n] = __builtin_amdgcn_mfma_f32_16x16x32_bf16(Bt[n][k], At[m][k], acc[ai][bj][m][n], 0, 0, 0); __builtin_amdgcn_s_setprio(0); } while (0)
; #define PG8_WAIT_V(n) asm volatile("s_waitcnt vmcnt(" #n ")" ::: "memory")
; #define PG8_WAIT_L(n) asm volatile("s_waitcnt lgkmcnt(" #n ")" ::: "memory")
; template <class Epi, class Sched, bool ALIGN_EPI = false, bool SP2 = false>
; __device__ __forceinline__ void gemm_phase(PG8_LAS unsigned char* lds, const Gemm g, const Sched& S, const Epi& E) {
;     ...
;             const bool last = (t == nt - 2);
;             const char* a1 = cA + (size_t)(t + 1) * kstep;
;             const char* a2 = last ? nA : cA + (size_t)(t + 2) * kstep; const char* b2 = last ? nB : cB + (size_t)(t + 2) * kstep;
;             const char* a3 = a2 + kstep; const char* b3 = b2 + kstep;
;             if (last && has_next) S.a_ready(nxt);
;             if constexpr (SP2) {
;             PG8_LDB(B0, 0, 0); PG8_LDB(B1, 0, 1); PG8_SCHED; PG8_LDA(At, 0, 0); PG8_STAGE(PG8_SA(1, 1), a1 + hstep, voffA);
;             PG8_WAIT_V(8); PG8_WAIT_L(0); PG8_BAR; PG8_MMA(0, 0, At, B0); PG8_MMA(0, 1, At, B1); PG8_BAR; PG8_SCHED;
;             PG8_LDA(At, 0, 1); PG8_STAGE(PG8_SB(0, 0), b2, voffB); PG8_STAGE(PG8_SB(0, 1), b2 + hstep, voffB); PG8_STAGE(PG8_SA(0, 0), a2, voffA);
;             PG8_WAIT_V(8); PG8_WAIT_L(0); PG8_BAR; PG8_MMA(1, 0, At, B0); PG8_MMA(1, 1, At, B1); PG8_BAR; PG8_SCHED;
.LBB0_883:
	s_add_u32 s18, s16, 0xfffc0080
	s_addc_u32 s19, s17, -1
	s_add_i32 s40, 0, 0x10000
	s_cmp_eq_u32 s39, 12
	s_cselect_b32 s21, s11, s19
	s_cselect_b32 s20, s33, s18
	s_cselect_b32 s19, s9, s38
	s_cselect_b32 s18, s34, s35
	s_add_i32 s46, 0, 0x14000
	v_add_u32_e32 v156, s40, v141
	v_add_u32_e32 v172, s46, v141
	ds_read_b128 v[144:147], v156
	ds_read_b128 v[148:151], v156 offset:1024
	ds_read_b128 v[152:155], v156 offset:2048
	ds_read_b128 v[156:159], v156 offset:3072
	ds_read_b128 v[160:163], v172
	ds_read_b128 v[164:167], v172 offset:1024
	ds_read_b128 v[168:171], v172 offset:2048
	ds_read_b128 v[172:175], v172 offset:3072
	v_lshl_add_u64 v[216:217], s[16:17], 0, v[136:137]
	s_add_i32 m0, s23, 0xc000
	ds_read_b128 v[176:179], v143
	ds_read_b128 v[180:183], v143 offset:1024
	ds_read_b128 v[184:187], v143 offset:2048
	ds_read_b128 v[188:191], v143 offset:3072
	ds_read_b128 v[192:195], v143 offset:4096
	ds_read_b128 v[204:207], v143 offset:5120
	ds_read_b128 v[208:211], v143 offset:6144
	ds_read_b128 v[212:215], v143 offset:7168
	global_load_lds_dwordx4 v[216:217], off
	v_lshl_add_u64 v[216:217], s[16:17], 0, v[138:139]
	s_add_i32 m0, s23, 0xe000
	s_nop 0
	global_load_lds_dwordx4 v[216:217], off
	s_waitcnt vmcnt(8)
	s_waitcnt lgkmcnt(0)
	s_setprio 1
	s_barrier
	v_mfma_f32_16x16x32_bf16 v[128:131], v[144:147], v[176:179], v[128:131]
	v_mfma_f32_16x16x32_bf16 v[124:127], v[152:155], v[176:179], v[124:127]
	v_mfma_f32_16x16x32_bf16 v[112:115], v[144:147], v[184:187], v[112:115]
	v_mfma_f32_16x16x32_bf16 v[108:111], v[152:155], v[184:187], v[108:111]
	v_mfma_f32_16x16x32_bf16 v[96:99], v[144:147], v[192:195], v[96:99]
	v_mfma_f32_16x16x32_bf16 v[92:95], v[152:155], v[192:195], v[92:95]
	v_mfma_f32_16x16x32_bf16 v[80:83], v[144:147], v[208:211], v[80:83]
	v_mfma_f32_16x16x32_bf16 v[76:79], v[152:155], v[208:211], v[76:79]
	v_mfma_f32_16x16x32_bf16 v[128:131], v[148:151], v[180:183], v[128:131]
	v_mfma_f32_16x16x32_bf16 v[124:127], v[156:159], v[180:183], v[124:127]
	v_mfma_f32_16x16x32_bf16 v[112:115], v[148:151], v[188:191], v[112:115]
	v_mfma_f32_16x16x32_bf16 v[108:111], v[156:159], v[188:191], v[108:111]
	v_mfma_f32_16x16x32_bf16 v[96:99], v[148:151], v[204:207], v[96:99]
	v_mfma_f32_16x16x32_bf16 v[92:95], v[156:159], v[204:207], v[92:95]
	v_mfma_f32_16x16x32_bf16 v[80:83], v[148:151], v[212:215], v[80:83]
	v_mfma_f32_16x16x32_bf16 v[76:79], v[156:159], v[212:215], v[76:79]
	v_mfma_f32_16x16x32_bf16 v[120:123], v[160:163], v[176:179], v[120:123]
	v_mfma_f32_16x16x32_bf16 v[116:119], v[168:171], v[176:179], v[116:119]
	v_mfma_f32_16x16x32_bf16 v[104:107], v[160:163], v[184:187], v[104:107]
	v_mfma_f32_16x16x32_bf16 v[100:103], v[168:171], v[184:187], v[100:103]
	v_mfma_f32_16x16x32_bf16 v[88:91], v[160:163], v[192:195], v[88:91]
	v_mfma_f32_16x16x32_bf16 v[84:87], v[168:171], v[192:195], v[84:87]
	v_mfma_f32_16x16x32_bf16 v[72:75], v[160:163], v[208:211], v[72:75]
	v_mfma_f32_16x16x32_bf16 v[68:71], v[168:171], v[208:211], v[68:71]
	v_mfma_f32_16x16x32_bf16 v[120:123], v[164:167], v[180:183], v[120:123]
	v_mfma_f32_16x16x32_bf16 v[116:119], v[172:175], v[180:183], v[116:119]
	v_mfma_f32_16x16x32_bf16 v[104:107], v[164:167], v[188:191], v[104:107]
	v_mfma_f32_16x16x32_bf16 v[100:103], v[172:175], v[188:191], v[100:103]
	v_mfma_f32_16x16x32_bf16 v[88:91], v[164:167], v[204:207], v[88:91]
	v_mfma_f32_16x16x32_bf16 v[84:87], v[172:175], v[204:207], v[84:87]
	v_mfma_f32_16x16x32_bf16 v[72:75], v[164:167], v[212:215], v[72:75]
	v_mfma_f32_16x16x32_bf16 v[68:71], v[172:175], v[212:215], v[68:71]
	s_barrier
	s_setprio 0
	s_add_i32 s40, s40, s22
	v_lshl_add_u64 v[216:217], s[18:19], 0, v[2:3]
	s_mov_b32 m0, s40
	ds_read_b128 v[176:179], v143 offset:16384
	ds_read_b128 v[180:183], v143 offset:17408
	ds_read_b128 v[184:187], v143 offset:18432
	ds_read_b128 v[188:191], v143 offset:19456
	ds_read_b128 v[192:195], v143 offset:20480
	ds_read_b128 v[204:207], v143 offset:21504
	ds_read_b128 v[208:211], v143 offset:22528
	ds_read_b128 v[212:215], v143 offset:23552
	global_load_lds_dwordx4 v[216:217], off
	s_add_i32 m0, s40, 0x2000
	s_add_u32 s40, s18, 0x40000
	v_lshl_add_u64 v[218:219], s[18:19], 0, v[0:1]
	s_addc_u32 s41, s19, 0
	s_add_i32 s46, s46, s22
	global_load_lds_dwordx4 v[218:219], off
	v_lshl_add_u64 v[236:237], s[40:41], 0, v[2:3]
	s_mov_b32 m0, s46
	v_lshl_add_u64 v[238:239], s[20:21], 0, v[132:133]
	global_load_lds_dwordx4 v[236:237], off
	v_lshl_add_u64 v[236:237], s[40:41], 0, v[0:1]
	s_add_i32 m0, s46, 0x2000
	s_nop 0
	global_load_lds_dwordx4 v[236:237], off
	v_lshl_add_u64 v[236:237], s[20:21], 0, v[134:135]
	s_mov_b32 m0, s23
	s_nop 0
	global_load_lds_dwordx4 v[236:237], off
	s_mov_b32 m0, s24
	s_nop 0
	global_load_lds_dwordx4 v[238:239], off
	s_waitcnt vmcnt(8)
	s_waitcnt lgkmcnt(0)
	s_setprio 1
	s_barrier
; #define PG8_STAGE(bufoff, gbase, voff) do { _Pragma("unroll") for (int _i = 0; _i < 2; ++_i) \
;         __builtin_amdgcn_global_load_lds((const unsigned*)((const char*)(gbase) + (voff)[_i]), (PG8_LAS unsigned*)(lds + (bufoff) + ldsw + _i * 8192), 16, 0, 0); } while (0)
; #define PG8_LDA(dst, b, h) do { _Pragma("unroll") for (int m = 0; m < 4; ++m) _Pragma("unroll") for (int k = 0; k < 2; ++k) dst[m][k] = *(const PG8_LAS bf16x8*)(lds + PG8_SA(b, h) + aoff + m * 2048 + k * 1024); } while (0)
; #define PG8_LDB(dst, b, h) do { _Pragma("unroll") for (int n = 0; n < 2; ++n) _Pragma("unroll") for (int k = 0; k < 2; ++k) dst[n][k] = *(const PG8_LAS bf16x8*)(lds + PG8_SB(b, h) + boff + n * 2048 + k * 1024); } while (0)
; #define PG8_MMA(ai, bj, At, Bt) do { __builtin_amdgcn_s_setprio(1); _Pragma("unroll") for (int m = 0; m < 4; ++m) _Pragma("unroll") for (int n = 0; n < 2; ++n) _Pragma("unroll") for (int k = 0; k < 2; ++k) \
;         acc[ai][bj][m][n] = __builtin_amdgcn_mfma_f32_16x16x32_bf16(Bt[n][k], At[m][k], acc[ai][bj][m][n], 0, 0, 0); __builtin_amdgcn_s_setprio(0); } while (0)
; #define PG8_WAIT_V(n) asm volatile("s_waitcnt vmcnt(" #n ")" ::: "memory")
; #define PG8_WAIT_L(n) asm volatile("s_waitcnt lgkmcnt(" #n ")" ::: "memory")
; #define PG8_BAR __builtin_amdgcn_s_barrier()
; #define PG8_SCHED __builtin_amdgcn_sched_barrier(0)
; template <class Epi, class Sched, bool ALIGN_EPI = false, bool SP2 = false>
; __device__ __forceinline__ void gemm_phase(PG8_LAS unsigned char* lds, const Gemm g, const Sched& S, const Epi& E) {
;     ...
;             PG8_WAIT_V(8); PG8_WAIT_L(0); PG8_BAR; PG8_MMA(1, 0, At, B0); PG8_MMA(1, 1, At, B1); PG8_BAR; PG8_SCHED;
;             PG8_LDB(B0, 1, 0); PG8_LDB(B1, 1, 1); PG8_SCHED; PG8_LDA(At, 1, 0); PG8_STAGE(PG8_SA(0, 1), a2 + hstep, voffA);
;             PG8_WAIT_V(8); PG8_WAIT_L(0); PG8_BAR; PG8_MMA(0, 0, At, B0); PG8_MMA(0, 1, At, B1); PG8_BAR; PG8_SCHED;
	v_mfma_f32_16x16x32_bf16 v[64:67], v[144:147], v[176:179], v[64:67]
	v_mfma_f32_16x16x32_bf16 v[60:63], v[152:155], v[176:179], v[60:63]
	v_mfma_f32_16x16x32_bf16 v[48:51], v[144:147], v[184:187], v[48:51]
	v_mfma_f32_16x16x32_bf16 v[44:47], v[152:155], v[184:187], v[44:47]
	v_mfma_f32_16x16x32_bf16 v[32:35], v[144:147], v[192:195], v[32:35]
	v_mfma_f32_16x16x32_bf16 v[28:31], v[152:155], v[192:195], v[28:31]
	v_mfma_f32_16x16x32_bf16 v[16:19], v[144:147], v[208:211], v[16:19]
	v_mfma_f32_16x16x32_bf16 v[12:15], v[152:155], v[208:211], v[12:15]
	v_mfma_f32_16x16x32_bf16 v[64:67], v[148:151], v[180:183], v[64:67]
	v_mfma_f32_16x16x32_bf16 v[60:63], v[156:159], v[180:183], v[60:63]
	v_mfma_f32_16x16x32_bf16 v[48:51], v[148:151], v[188:191], v[48:51]
	v_mfma_f32_16x16x32_bf16 v[44:47], v[156:159], v[188:191], v[44:47]
	v_mfma_f32_16x16x32_bf16 v[32:35], v[148:151], v[204:207], v[32:35]
	v_mfma_f32_16x16x32_bf16 v[28:31], v[156:159], v[204:207], v[28:31]
	v_mfma_f32_16x16x32_bf16 v[16:19], v[148:151], v[212:215], v[16:19]
	v_mfma_f32_16x16x32_bf16 v[12:15], v[156:159], v[212:215], v[12:15]
	v_mfma_f32_16x16x32_bf16 v[56:59], v[160:163], v[176:179], v[56:59]
	v_mfma_f32_16x16x32_bf16 v[52:55], v[168:171], v[176:179], v[52:55]
	v_mfma_f32_16x16x32_bf16 v[40:43], v[160:163], v[184:187], v[40:43]
	v_mfma_f32_16x16x32_bf16 v[36:39], v[168:171], v[184:187], v[36:39]
	v_mfma_f32_16x16x32_bf16 v[24:27], v[160:163], v[192:195], v[24:27]
	v_mfma_f32_16x16x32_bf16 v[20:23], v[168:171], v[192:195], v[20:23]
	v_mfma_f32_16x16x32_bf16 v[8:11], v[160:163], v[208:211], v[8:11]
	v_mfma_f32_16x16x32_bf16 v[4:7], v[168:171], v[208:211], v[4:7]
	v_mfma_f32_16x16x32_bf16 v[56:59], v[164:167], v[180:183], v[56:59]
	v_mfma_f32_16x16x32_bf16 v[52:55], v[172:175], v[180:183], v[52:55]
	v_mfma_f32_16x16x32_bf16 v[40:43], v[164:167], v[188:191], v[40:43]
	v_mfma_f32_16x16x32_bf16 v[36:39], v[172:175], v[188:191], v[36:39]
	v_mfma_f32_16x16x32_bf16 v[24:27], v[164:167], v[204:207], v[24:27]
	v_mfma_f32_16x16x32_bf16 v[20:23], v[172:175], v[204:207], v[20:23]
	v_mfma_f32_16x16x32_bf16 v[8:11], v[164:167], v[212:215], v[8:11]
	v_mfma_f32_16x16x32_bf16 v[4:7], v[172:175], v[212:215], v[4:7]
	s_barrier
	s_setprio 0
	s_add_i32 s40, 0, 0x18000
	s_add_i32 s41, 0, 0x1c000
	v_add_u32_e32 v156, s40, v141
	v_add_u32_e32 v172, s41, v141
	ds_read_b128 v[144:147], v156
	ds_read_b128 v[148:151], v156 offset:1024
	ds_read_b128 v[152:155], v156 offset:2048
	ds_read_b128 v[156:159], v156 offset:3072
	ds_read_b128 v[160:163], v172
	ds_read_b128 v[164:167], v172 offset:1024
	ds_read_b128 v[168:171], v172 offset:2048
	ds_read_b128 v[172:175], v172 offset:3072
	s_add_u32 s20, s20, 0x40000
	s_addc_u32 s21, s21, 0
	s_mov_b32 m0, s25
	v_lshl_add_u64 v[240:241], s[20:21], 0, v[134:135]
	ds_read_b128 v[176:179], v143 offset:32768
	ds_read_b128 v[180:183], v143 offset:33792
	ds_read_b128 v[184:187], v143 offset:34816
	ds_read_b128 v[188:191], v143 offset:35840
	ds_read_b128 v[192:195], v143 offset:36864
	ds_read_b128 v[204:207], v143 offset:37888
	ds_read_b128 v[208:211], v143 offset:38912
	ds_read_b128 v[212:215], v143 offset:39936
	global_load_lds_dwordx4 v[240:241], off
	v_lshl_add_u64 v[240:241], s[20:21], 0, v[132:133]
	s_mov_b32 m0, s26
	s_nop 0
	global_load_lds_dwordx4 v[240:241], off
	s_waitcnt vmcnt(8)
	s_waitcnt lgkmcnt(0)
	s_setprio 1
	s_barrier
	v_mfma_f32_16x16x32_bf16 v[128:131], v[144:147], v[176:179], v[128:131]
	v_mfma_f32_16x16x32_bf16 v[124:127], v[152:155], v[176:179], v[124:127]
	v_mfma_f32_16x16x32_bf16 v[112:115], v[144:147], v[184:187], v[112:115]
	v_mfma_f32_16x16x32_bf16 v[108:111], v[152:155], v[184:187], v[108:111]
	v_mfma_f32_16x16x32_bf16 v[96:99], v[144:147], v[192:195], v[96:99]
	v_mfma_f32_16x16x32_bf16 v[92:95], v[152:155], v[192:195], v[92:95]
	v_mfma_f32_16x16x32_bf16 v[80:83], v[144:147], v[208:211], v[80:83]
	v_mfma_f32_16x16x32_bf16 v[76:79], v[152:155], v[208:211], v[76:79]
	v_mfma_f32_16x16x32_bf16 v[128:131], v[148:151], v[180:183], v[128:131]
	v_mfma_f32_16x16x32_bf16 v[124:127], v[156:159], v[180:183], v[124:127]
	v_mfma_f32_16x16x32_bf16 v[112:115], v[148:151], v[188:191], v[112:115]
	v_mfma_f32_16x16x32_bf16 v[108:111], v[156:159], v[188:191], v[108:111]
	v_mfma_f32_16x16x32_bf16 v[96:99], v[148:151], v[204:207], v[96:99]
	v_mfma_f32_16x16x32_bf16 v[92:95], v[156:159], v[204:207], v[92:95]
	v_mfma_f32_16x16x32_bf16 v[80:83], v[148:151], v[212:215], v[80:83]
	v_mfma_f32_16x16x32_bf16 v[76:79], v[156:159], v[212:215], v[76:79]
	v_mfma_f32_16x16x32_bf16 v[120:123], v[160:163], v[176:179], v[120:123]
	v_mfma_f32_16x16x32_bf16 v[116:119], v[168:171], v[176:179], v[116:119]
	v_mfma_f32_16x16x32_bf16 v[104:107], v[160:163], v[184:187], v[104:107]
	v_mfma_f32_16x16x32_bf16 v[100:103], v[168:171], v[184:187], v[100:103]
	v_mfma_f32_16x16x32_bf16 v[88:91], v[160:163], v[192:195], v[88:91]
	v_mfma_f32_16x16x32_bf16 v[84:87], v[168:171], v[192:195], v[84:87]
	v_mfma_f32_16x16x32_bf16 v[72:75], v[160:163], v[208:211], v[72:75]
	v_mfma_f32_16x16x32_bf16 v[68:71], v[168:171], v[208:211], v[68:71]
	v_mfma_f32_16x16x32_bf16 v[120:123], v[164:167], v[180:183], v[120:123]
	v_mfma_f32_16x16x32_bf16 v[116:119], v[172:175], v[180:183], v[116:119]
	v_mfma_f32_16x16x32_bf16 v[104:107], v[164:167], v[188:191], v[104:107]
	v_mfma_f32_16x16x32_bf16 v[100:103], v[172:175], v[188:191], v[100:103]
	v_mfma_f32_16x16x32_bf16 v[88:91], v[164:167], v[204:207], v[88:91]
	v_mfma_f32_16x16x32_bf16 v[84:87], v[172:175], v[204:207], v[84:87]
	v_mfma_f32_16x16x32_bf16 v[72:75], v[164:167], v[212:215], v[72:75]
	v_mfma_f32_16x16x32_bf16 v[68:71], v[172:175], v[212:215], v[68:71]
	s_barrier
; #define PG8_STAGE(bufoff, gbase, voff) do { _Pragma("unroll") for (int _i = 0; _i < 2; ++_i) \
;         __builtin_amdgcn_global_load_lds((const unsigned*)((const char*)(gbase) + (voff)[_i]), (PG8_LAS unsigned*)(lds + (bufoff) + ldsw + _i * 8192), 16, 0, 0); } while (0)
; #define PG8_LDA(dst, b, h) do { _Pragma("unroll") for (int m = 0; m < 4; ++m) _Pragma("unroll") for (int k = 0; k < 2; ++k) dst[m][k] = *(const PG8_LAS bf16x8*)(lds + PG8_SA(b, h) + aoff + m * 2048 + k * 1024); } while (0)
; #define PG8_MMA(ai, bj, At, Bt) do { __builtin_amdgcn_s_setprio(1); _Pragma("unroll") for (int m = 0; m < 4; ++m) _Pragma("unroll") for (int n = 0; n < 2; ++n) _Pragma("unroll") for (int k = 0; k < 2; ++k) \
;         acc[ai][bj][m][n] = __builtin_amdgcn_mfma_f32_16x16x32_bf16(Bt[n][k], At[m][k], acc[ai][bj][m][n], 0, 0, 0); __builtin_amdgcn_s_setprio(0); } while (0)
; #define PG8_WAIT_V(n) asm volatile("s_waitcnt vmcnt(" #n ")" ::: "memory")
; #define PG8_WAIT_L(n) asm volatile("s_waitcnt lgkmcnt(" #n ")" ::: "memory")
; #define PG8_BAR __builtin_amdgcn_s_barrier()
; #define PG8_SCHED __builtin_amdgcn_sched_barrier(0)
; template <class Epi, class Sched, bool ALIGN_EPI = false, bool SP2 = false>
; __device__ __forceinline__ void gemm_phase(PG8_LAS unsigned char* lds, const Gemm g, const Sched& S, const Epi& E) {
;     ...
;             PG8_LDA(At, 1, 1); PG8_STAGE(PG8_SB(1, 0), b3, voffB); PG8_STAGE(PG8_SB(1, 1), b3 + hstep, voffB); PG8_STAGE(PG8_SA(1, 0), a3, voffA);
;             PG8_WAIT_V(8); PG8_WAIT_L(0); PG8_BAR; PG8_MMA(1, 0, At, B0); PG8_MMA(1, 1, At, B1); PG8_BAR; PG8_SCHED;
	s_setprio 0
	s_add_i32 s20, s40, s22
	v_lshl_add_u64 v[216:217], v[216:217], 0, s[42:43]
	s_mov_b32 m0, s20
	ds_read_b128 v[176:179], v143 offset:49152
	ds_read_b128 v[180:183], v143 offset:50176
	ds_read_b128 v[184:187], v143 offset:51200
	ds_read_b128 v[188:191], v143 offset:52224
	ds_read_b128 v[192:195], v143 offset:53248
	ds_read_b128 v[204:207], v143 offset:54272
	ds_read_b128 v[208:211], v143 offset:55296
	ds_read_b128 v[212:215], v143 offset:56320
	global_load_lds_dwordx4 v[216:217], off
	s_add_i32 m0, s20, 0x2000
	s_add_u32 s18, s18, 0x40080
	v_lshl_add_u64 v[216:217], v[218:219], 0, s[42:43]
	s_addc_u32 s19, s19, 0
	s_add_i32 s20, s41, s22
	global_load_lds_dwordx4 v[216:217], off
	v_lshl_add_u64 v[216:217], s[18:19], 0, v[2:3]
	s_mov_b32 m0, s20
	s_nop 0
	global_load_lds_dwordx4 v[216:217], off
	v_lshl_add_u64 v[216:217], s[18:19], 0, v[0:1]
	s_add_i32 m0, s20, 0x2000
	s_nop 0
	global_load_lds_dwordx4 v[216:217], off
	v_lshl_add_u64 v[216:217], v[236:237], 0, s[42:43]
	s_mov_b32 m0, s27
	s_nop 0
	global_load_lds_dwordx4 v[216:217], off
	v_lshl_add_u64 v[216:217], v[238:239], 0, s[42:43]
	s_mov_b32 m0, s28
	s_nop 0
	global_load_lds_dwordx4 v[216:217], off
	s_waitcnt vmcnt(8)
	s_waitcnt lgkmcnt(0)
	s_setprio 1
	s_barrier
	v_mfma_f32_16x16x32_bf16 v[64:67], v[144:147], v[176:179], v[64:67]
	v_mfma_f32_16x16x32_bf16 v[60:63], v[152:155], v[176:179], v[60:63]
	v_mfma_f32_16x16x32_bf16 v[48:51], v[144:147], v[184:187], v[48:51]
	v_mfma_f32_16x16x32_bf16 v[44:47], v[152:155], v[184:187], v[44:47]
	v_mfma_f32_16x16x32_bf16 v[32:35], v[144:147], v[192:195], v[32:35]
	v_mfma_f32_16x16x32_bf16 v[28:31], v[152:155], v[192:195], v[28:31]
	v_mfma_f32_16x16x32_bf16 v[16:19], v[144:147], v[208:211], v[16:19]
	v_mfma_f32_16x16x32_bf16 v[12:15], v[152:155], v[208:211], v[12:15]
	v_mfma_f32_16x16x32_bf16 v[64:67], v[148:151], v[180:183], v[64:67]
	v_mfma_f32_16x16x32_bf16 v[60:63], v[156:159], v[180:183], v[60:63]
	v_mfma_f32_16x16x32_bf16 v[48:51], v[148:151], v[188:191], v[48:51]
	v_mfma_f32_16x16x32_bf16 v[44:47], v[156:159], v[188:191], v[44:47]
	v_mfma_f32_16x16x32_bf16 v[32:35], v[148:151], v[204:207], v[32:35]
	v_mfma_f32_16x16x32_bf16 v[28:31], v[156:159], v[204:207], v[28:31]
	v_mfma_f32_16x16x32_bf16 v[16:19], v[148:151], v[212:215], v[16:19]
	v_mfma_f32_16x16x32_bf16 v[12:15], v[156:159], v[212:215], v[12:15]
	v_mfma_f32_16x16x32_bf16 v[56:59], v[160:163], v[176:179], v[56:59]
	v_mfma_f32_16x16x32_bf16 v[52:55], v[168:171], v[176:179], v[52:55]
	v_mfma_f32_16x16x32_bf16 v[40:43], v[160:163], v[184:187], v[40:43]
	v_mfma_f32_16x16x32_bf16 v[36:39], v[168:171], v[184:187], v[36:39]
	v_mfma_f32_16x16x32_bf16 v[24:27], v[160:163], v[192:195], v[24:27]
	v_mfma_f32_16x16x32_bf16 v[20:23], v[168:171], v[192:195], v[20:23]
	v_mfma_f32_16x16x32_bf16 v[8:11], v[160:163], v[208:211], v[8:11]
	v_mfma_f32_16x16x32_bf16 v[4:7], v[168:171], v[208:211], v[4:7]
	v_mfma_f32_16x16x32_bf16 v[56:59], v[164:167], v[180:183], v[56:59]
	v_mfma_f32_16x16x32_bf16 v[52:55], v[172:175], v[180:183], v[52:55]
	v_mfma_f32_16x16x32_bf16 v[40:43], v[164:167], v[188:191], v[40:43]
	v_mfma_f32_16x16x32_bf16 v[36:39], v[172:175], v[188:191], v[36:39]
	v_mfma_f32_16x16x32_bf16 v[24:27], v[164:167], v[204:207], v[24:27]
	v_mfma_f32_16x16x32_bf16 v[20:23], v[172:175], v[204:207], v[20:23]
	v_mfma_f32_16x16x32_bf16 v[8:11], v[164:167], v[212:215], v[8:11]
	v_mfma_f32_16x16x32_bf16 v[4:7], v[172:175], v[212:215], v[4:7]
	s_barrier
	s_setprio 0
	s_add_i32 s39, s39, 2
	s_add_u32 s16, s16, 0x100
	s_addc_u32 s17, s17, 0
	s_add_u32 s35, s35, 0x100
	s_addc_u32 s38, s38, 0
	s_cmp_gt_u32 s39, 13
	s_cbranch_scc0 .LBB0_883
	s_and_b64 vcc, exec, s[6:7]
	s_cbranch_vccz .LBB0_886
	s_barrier
